# P6 epilogue loads up front + P6 workgroup groups staggered by 5us at phase start
# baseline (speedup 1.0000x reference)
; __device__ __forceinline__ void xcd_barrier(const XcdBarrier& b) {
;     ...
;     __syncthreads();
; }
.LBB0_1345:
	s_or_b64 exec, exec, s[4:5]
	v_mov_b32_e32 v166, v230
	s_waitcnt lgkmcnt(0)
	s_barrier
	s_bfe_u32 s98, s2, 0x20003
	s_mul_i32 s98, s98, 500
	s_cmp_eq_u32 s98, 0
	s_cbranch_scc1 .Lmy_dly_done_9
	s_memrealtime s[100:101]
	s_waitcnt lgkmcnt(0)
	s_add_u32 s98, s100, s98
.Lmy_dly_9:
	s_sleep 1
	s_memrealtime s[100:101]
	s_waitcnt lgkmcnt(0)
	s_sub_u32 s99, s100, s98
	s_cmp_lt_i32 s99, 0
	s_cbranch_scc1 .Lmy_dly_9
.Lmy_dly_done_9:
	s_and_b32 s0, s14, 7
	s_cmp_lg_u32 s0, 0
	s_mov_b32 s15, s2
	s_cbranch_scc1 .LBB0_1347
	s_ashr_i32 s1, s2, 31
	s_lshr_b32 s1, s1, 29
	s_add_i32 s1, s2, s1
	s_and_b32 s3, s1, -8
	s_ashr_i32 s0, s14, 3
	s_sub_i32 s3, s2, s3
	s_mul_i32 s0, s3, s0
	s_ashr_i32 s1, s1, 3
	s_add_i32 s15, s0, s1
